# grid barrier skipped after the two phases that do no work (odd layers have no hgrn_scan step); rest unchanged
# baseline (speedup 1.0000x reference)
; DI void xcd_barrier(const XcdBarrier& b) {
;   asm volatile("s_waitcnt vmcnt(0)" ::: "memory");
;   __syncthreads();
;   if (threadIdx.x == 0) {
;     unsigned* bar = b.bar;
;     __builtin_amdgcn_s_waitcnt(0);
;     unsigned nloc = b.st[0], nx = b.st[1];
;     if (nloc == 0u) { xcd_barrier_complete(bar, b.x, nloc, nx); b.st[0] = nloc; b.st[1] = nx; }
; __global__ void __launch_bounds__(NTH) fwd_megakernel(Params p) {
;     ...
;   for (int ph = p.ph_lo; ph < p.ph_hi; ++ph) {
;     if (ph >= PH_PRE && (((ph - PH_PRE) / PH_PER_LAYER) & 1) == 1 && (ph - PH_PRE) % PH_PER_LAYER == 3) continue;
;     run_phase(p, ph);
;     if (ph + 1 < p.ph_hi) { if (ph == 0) grid.sync(); else xcd_barrier(xb); }
.LBB0_2667:
	s_add_i32 s16, s78, 1
	s_cmp_ge_i32 s16, s79
	s_cbranch_scc1 .LBB0_2681
	s_cmp_eq_u32 s78, 15
	s_cbranch_scc1 .LBB0_2681
	s_cmp_eq_u32 s78, 37
	s_cbranch_scc1 .LBB0_2681
	v_readlane_b32 s0, v253, 46
	v_readlane_b32 s1, v253, 47
	s_and_b64 vcc, exec, s[0:1]
	s_nop 0
	s_waitcnt vmcnt(0)
	s_waitcnt lgkmcnt(0)
	s_barrier
	s_mov_b64 s[0:1], exec
	v_readlane_b32 s2, v250, 5
	v_readlane_b32 s3, v250, 6
	s_and_b64 s[2:3], s[0:1], s[2:3]
	s_mov_b64 exec, s[2:3]
	s_cbranch_execz .LBB0_2723
	v_readlane_b32 s2, v253, 8
	s_waitcnt vmcnt(0) expcnt(0) lgkmcnt(0)
	s_nop 0
	v_mov_b32_e32 v0, s2
	ds_read_b32 v3, v0
	v_readlane_b32 s2, v253, 9
	s_waitcnt lgkmcnt(0)
	v_cmp_ne_u32_e32 vcc, 0, v3
	v_mov_b32_e32 v0, s2
	ds_read_b32 v2, v0
	s_cbranch_vccnz .LBB0_2687
	s_mov_b32 s8, 1
	s_branch .LBB0_2673
